# dilated attention: dense group staged once per block in an LDS ring (shared by 8 waves), strided groups prefetched per wave with per-tile barrier
# speedup vs baseline: 1.0068x; 1.0068x over previous
.Ldil_pro:
	v_mul_u32_u24_e32 v199, 0x60, v243
	ds_write_b128 v199, v[148:151]
	ds_write_b128 v199, v[152:155] offset:16
	ds_write_b128 v199, v[156:159] offset:32
	ds_write_b128 v199, v[160:163] offset:48
	ds_write_b128 v199, v[164:167] offset:64
	s_cmp_eq_u32 s41, 0
	s_cbranch_scc1 .Ldil_g0
	v_lshlrev_b32_e32 v132, s42, v197
	v_ashrrev_i32_e32 v133, 31, v132
	v_lshlrev_b64 v[132:133], 7, v[132:133]
	v_lshl_add_u64 v[132:133], v[14:15], 0, v[132:133]
	global_load_dwordx4 v[144:147], v[132:133], off offset:96
	global_load_dwordx4 v[140:143], v[132:133], off offset:64
	global_load_dwordx4 v[136:139], v[132:133], off offset:32
	s_nop 0
	global_load_dwordx4 v[132:135], v[132:133], off
	v_lshl_add_u64 v[236:237], v[236:237], 0, s[8:9]
	s_mov_b64 s[46:47], 0x2000
	v_lshl_add_u64 v[234:235], v[236:237], 0, s[46:47]
	global_load_dwordx4 v[214:217], v[236:237], off
	global_load_dwordx4 v[218:221], v[236:237], off offset:32
	global_load_dwordx4 v[222:225], v[236:237], off offset:2048
	global_load_dwordx4 v[226:229], v[236:237], off offset:2080
	global_load_dwordx4 v[230:233], v[234:235], off offset:-4096
	global_load_dwordx4 v[244:247], v[234:235], off offset:-4064
	global_load_dwordx4 v[248:251], v[234:235], off offset:-2048
	global_load_dwordx4 v[164:167], v[234:235], off offset:-2016
	global_load_dwordx4 v[148:151], v[234:235], off
	global_load_dwordx4 v[152:155], v[234:235], off offset:32
	global_load_dwordx4 v[156:159], v[234:235], off offset:2048
	global_load_dwordx4 v[200:203], v[234:235], off offset:2080
	s_waitcnt lgkmcnt(0)
.Ldil_top:
	s_barrier
	s_waitcnt vmcnt(12)
	s_nop 0
	v_mfma_f32_32x32x16_bf16 v[112:127], v[132:135], v[2:5], 0
	v_mfma_f32_32x32x16_bf16 v[112:127], v[136:139], v[6:9], v[112:127]
	v_mfma_f32_32x32x16_bf16 v[112:127], v[140:143], v[10:13], v[112:127]
	v_mfma_f32_32x32x16_bf16 v[112:127], v[144:147], v[128:131], v[112:127]
	s_add_i32 s44, s44, 1
	v_add_u32_e32 v197, 32, v197
	s_cmp_lt_i32 s44, s43
	s_cbranch_scc0 .Ldil_nok
	v_lshlrev_b32_e32 v132, s42, v197
	v_ashrrev_i32_e32 v133, 31, v132
	v_lshlrev_b64 v[132:133], 7, v[132:133]
	v_lshl_add_u64 v[132:133], v[14:15], 0, v[132:133]
	global_load_dwordx4 v[144:147], v[132:133], off offset:96
	global_load_dwordx4 v[140:143], v[132:133], off offset:64
	global_load_dwordx4 v[136:139], v[132:133], off offset:32
	s_nop 0
	global_load_dwordx4 v[132:135], v[132:133], off

.Ldil_g0:
	v_readfirstlane_b32 s48, v243
	v_lshl_add_u64 v[236:237], v[236:237], 0, s[8:9]
	v_lshlrev_b32_e32 v132, s42, v197
	v_ashrrev_i32_e32 v133, 31, v132
	v_lshlrev_b64 v[132:133], 7, v[132:133]
	v_lshl_add_u64 v[132:133], v[14:15], 0, v[132:133]
	s_lshr_b32 s48, s48, 6
	s_cmp_gt_u32 s48, 5
	s_cbranch_scc1 .Ldil_g0k
	s_lshl_b32 s46, s48, 11
	s_mov_b32 s47, 0
	v_lshl_add_u64 v[234:235], v[236:237], 0, s[46:47]
	s_mov_b32 s45, 0x3000
	s_branch .Ldil_g0s
.Ldil_g0k:
	s_add_i32 s46, s48, -6
	s_lshl_b32 s46, s46, 6
	s_mov_b32 s47, 0
	v_lshl_add_u64 v[234:235], v[132:133], 0, s[46:47]
	s_mov_b32 s45, 0x1000
.Ldil_g0s:
	v_lshl_add_u64 v[236:237], v[234:235], 0, 32
	s_lshl_b32 s52, s48, 11
	s_add_i32 s52, s52, 0xc000
	v_lshlrev_b32_e32 v199, 4, v242
	v_add_u32_e32 v199, 0xc000, v199
	s_sub_i32 s49, s43, s44
	s_mov_b32 s48, 0
	s_mov_b32 s46, 0
	s_waitcnt lgkmcnt(0)
	s_mov_b32 s47, 4
.Ldil_g0pi:
	s_cmp_eq_u32 s49, 0
	s_cbranch_scc1 .Ldil_g0top
	s_cmp_eq_u32 s47, 0
	s_cbranch_scc1 .Ldil_g0top
	s_add_i32 m0, s52, s48
	s_nop 0
	global_load_lds_dwordx4 v[234:235], off
	s_add_i32 m0, m0, 0x400
	s_nop 0
	global_load_lds_dwordx4 v[236:237], off
	v_add_co_u32_e32 v234, vcc, s45, v234
	s_nop 1
	v_addc_co_u32_e32 v235, vcc, 0, v235, vcc
	v_add_co_u32_e32 v236, vcc, s45, v236
	s_nop 1
	v_addc_co_u32_e32 v237, vcc, 0, v237, vcc
	s_add_i32 s48, s48, 0x4000
	s_cmp_eq_u32 s48, 0x14000
	s_cselect_b32 s48, 0, s48
	s_add_i32 s49, s49, -1
	s_add_i32 s47, s47, -1
	s_branch .Ldil_g0pi
.Ldil_g0top:
	s_sub_i32 s47, s43, s44
	s_cmp_gt_i32 s47, 3
	s_cbranch_scc1 .Ldil_g0w6
	s_cmp_eq_u32 s47, 3
	s_cbranch_scc1 .Ldil_g0w4
	s_cmp_eq_u32 s47, 2
	s_cbranch_scc1 .Ldil_g0w2
	s_waitcnt vmcnt(0)
	s_branch .Ldil_g0b
.Ldil_g0w2:
	s_waitcnt vmcnt(2)
	s_branch .Ldil_g0b
.Ldil_g0w4:
	s_waitcnt vmcnt(4)
	s_branch .Ldil_g0b
.Ldil_g0w6:
	s_waitcnt vmcnt(6)
.Ldil_g0b:
	s_barrier
	s_cmp_eq_u32 s49, 0
	s_cbranch_scc1 .Ldil_g0ni
	s_add_i32 m0, s52, s48
	s_nop 0
	global_load_lds_dwordx4 v[234:235], off
	s_add_i32 m0, m0, 0x400
	s_nop 0
	global_load_lds_dwordx4 v[236:237], off
	v_add_co_u32_e32 v234, vcc, s45, v234
	s_nop 1
	v_addc_co_u32_e32 v235, vcc, 0, v235, vcc
	v_add_co_u32_e32 v236, vcc, s45, v236
	s_nop 1
	v_addc_co_u32_e32 v237, vcc, 0, v237, vcc
	s_add_i32 s48, s48, 0x4000
	s_cmp_eq_u32 s48, 0x14000
	s_cselect_b32 s48, 0, s48
	s_add_i32 s49, s49, -1
.Ldil_g0ni:
	v_add_u32_e32 v203, s46, v199
	ds_read_b128 v[132:135], v203 offset:12288
	ds_read_b128 v[136:139], v203 offset:13312
	ds_read_b128 v[140:143], v203 offset:14336
	ds_read_b128 v[144:147], v203 offset:15360
	ds_read_b128 v[214:217], v203
	ds_read_b128 v[218:221], v203 offset:1024
	ds_read_b128 v[222:225], v203 offset:2048
	ds_read_b128 v[226:229], v203 offset:3072
	ds_read_b128 v[230:233], v203 offset:4096
	ds_read_b128 v[244:247], v203 offset:5120
	ds_read_b128 v[248:251], v203 offset:6144
	ds_read_b128 v[164:167], v203 offset:7168
	ds_read_b128 v[148:151], v203 offset:8192
	ds_read_b128 v[152:155], v203 offset:9216
	ds_read_b128 v[156:159], v203 offset:10240
	ds_read_b128 v[200:203], v203 offset:11264
	s_add_i32 s46, s46, 0x4000
	s_cmp_eq_u32 s46, 0x14000
	s_cselect_b32 s46, 0, s46
	s_waitcnt lgkmcnt(12)
	v_mfma_f32_32x32x16_bf16 v[112:127], v[132:135], v[2:5], 0
	v_mfma_f32_32x32x16_bf16 v[112:127], v[136:139], v[6:9], v[112:127]
	v_mfma_f32_32x32x16_bf16 v[112:127], v[140:143], v[10:13], v[112:127]
	v_mfma_f32_32x32x16_bf16 v[112:127], v[144:147], v[128:131], v[112:127]
	s_add_i32 s44, s44, 1
	s_nop 11
	v_max_f32_e32 v160, v113, v113
	v_max_f32_e32 v162, v112, v112
	v_max_f32_e32 v160, v162, v160
	v_max3_f32 v160, v160, v114, v115
	v_max3_f32 v160, v160, v116, v117
	v_max3_f32 v160, v160, v118, v119
	v_max3_f32 v160, v160, v120, v121
	v_max3_f32 v160, v160, v122, v123
	v_max3_f32 v160, v160, v124, v125
	v_max3_f32 v160, v160, v126, v127
	v_mov_b32_e32 v162, v160
	s_nop 1
	v_permlane32_swap_b32_e32 v160, v162
	v_max_f32_e32 v162, v162, v162
	v_max_f32_e32 v160, v160, v160
	v_max_f32_e32 v160, v160, v162
	v_add_f32_e32 v162, 0x42317218, v198
	v_cmp_gt_f32_e32 vcc, v160, v162
	s_cbranch_vccz .Ldil_g0soft
	s_nop 0
	v_cndmask_b32_e32 v162, v198, v160, vcc
	v_sub_f32_e32 v160, v198, v162
	v_mul_f32_e32 v160, 0x3e38aa3b, v160
	v_exp_f32_e32 v160, v160
	v_mov_b32_e32 v198, v162
	v_mul_f32_e32 v177, v177, v160
	v_pk_mul_f32 v[110:111], v[110:111], v[160:161] op_sel_hi:[1,0]
	v_pk_mul_f32 v[108:109], v[108:109], v[160:161] op_sel_hi:[1,0]
	v_pk_mul_f32 v[106:107], v[106:107], v[160:161] op_sel_hi:[1,0]
	v_pk_mul_f32 v[104:105], v[104:105], v[160:161] op_sel_hi:[1,0]
	v_pk_mul_f32 v[102:103], v[102:103], v[160:161] op_sel_hi:[1,0]
	v_pk_mul_f32 v[100:101], v[100:101], v[160:161] op_sel_hi:[1,0]
	v_pk_mul_f32 v[98:99], v[98:99], v[160:161] op_sel_hi:[1,0]
	v_pk_mul_f32 v[96:97], v[96:97], v[160:161] op_sel_hi:[1,0]
	v_pk_mul_f32 v[94:95], v[94:95], v[160:161] op_sel_hi:[1,0]
	v_pk_mul_f32 v[92:93], v[92:93], v[160:161] op_sel_hi:[1,0]
	v_pk_mul_f32 v[90:91], v[90:91], v[160:161] op_sel_hi:[1,0]
	v_pk_mul_f32 v[88:89], v[88:89], v[160:161] op_sel_hi:[1,0]
	v_pk_mul_f32 v[86:87], v[86:87], v[160:161] op_sel_hi:[1,0]
	v_pk_mul_f32 v[84:85], v[84:85], v[160:161] op_sel_hi:[1,0]
	v_pk_mul_f32 v[82:83], v[82:83], v[160:161] op_sel_hi:[1,0]
	v_pk_mul_f32 v[80:81], v[80:81], v[160:161] op_sel_hi:[1,0]
	v_pk_mul_f32 v[78:79], v[78:79], v[160:161] op_sel_hi:[1,0]
	v_pk_mul_f32 v[76:77], v[76:77], v[160:161] op_sel_hi:[1,0]
	v_pk_mul_f32 v[74:75], v[74:75], v[160:161] op_sel_hi:[1,0]
	v_pk_mul_f32 v[72:73], v[72:73], v[160:161] op_sel_hi:[1,0]
	v_pk_mul_f32 v[70:71], v[70:71], v[160:161] op_sel_hi:[1,0]
	v_pk_mul_f32 v[68:69], v[68:69], v[160:161] op_sel_hi:[1,0]
	v_pk_mul_f32 v[66:67], v[66:67], v[160:161] op_sel_hi:[1,0]
	v_pk_mul_f32 v[64:65], v[64:65], v[160:161] op_sel_hi:[1,0]
	v_pk_mul_f32 v[62:63], v[62:63], v[160:161] op_sel_hi:[1,0]
	v_pk_mul_f32 v[60:61], v[60:61], v[160:161] op_sel_hi:[1,0]
	v_pk_mul_f32 v[58:59], v[58:59], v[160:161] op_sel_hi:[1,0]
	v_pk_mul_f32 v[56:57], v[56:57], v[160:161] op_sel_hi:[1,0]
	v_pk_mul_f32 v[54:55], v[54:55], v[160:161] op_sel_hi:[1,0]
	v_pk_mul_f32 v[52:53], v[52:53], v[160:161] op_sel_hi:[1,0]
	v_pk_mul_f32 v[50:51], v[50:51], v[160:161] op_sel_hi:[1,0]
	v_pk_mul_f32 v[48:49], v[48:49], v[160:161] op_sel_hi:[1,0]
	v_pk_mul_f32 v[46:47], v[46:47], v[160:161] op_sel_hi:[1,0]
	v_pk_mul_f32 v[44:45], v[44:45], v[160:161] op_sel_hi:[1,0]
	v_pk_mul_f32 v[42:43], v[42:43], v[160:161] op_sel_hi:[1,0]
	v_pk_mul_f32 v[40:41], v[40:41], v[160:161] op_sel_hi:[1,0]
	v_pk_mul_f32 v[38:39], v[38:39], v[160:161] op_sel_hi:[1,0]
	v_pk_mul_f32 v[36:37], v[36:37], v[160:161] op_sel_hi:[1,0]
	v_pk_mul_f32 v[34:35], v[34:35], v[160:161] op_sel_hi:[1,0]
	v_pk_mul_f32 v[32:33], v[32:33], v[160:161] op_sel_hi:[1,0]
	v_pk_mul_f32 v[30:31], v[30:31], v[160:161] op_sel_hi:[1,0]
	v_pk_mul_f32 v[28:29], v[28:29], v[160:161] op_sel_hi:[1,0]
	v_pk_mul_f32 v[26:27], v[26:27], v[160:161] op_sel_hi:[1,0]
	v_pk_mul_f32 v[24:25], v[24:25], v[160:161] op_sel_hi:[1,0]
	v_pk_mul_f32 v[22:23], v[22:23], v[160:161] op_sel_hi:[1,0]
	v_pk_mul_f32 v[20:21], v[20:21], v[160:161] op_sel_hi:[1,0]
	v_pk_mul_f32 v[18:19], v[18:19], v[160:161] op_sel_hi:[1,0]
	v_pk_mul_f32 v[16:17], v[16:17], v[160:161] op_sel_hi:[1,0]
.Ldil_g0soft:
	v_mul_f32_e32 v160, 0xbe38aa3b, v198
	v_fmamk_f32 v112, v112, 0x3e38aa3b, v160
	v_exp_f32_e32 v112, v112
	v_fmamk_f32 v113, v113, 0x3e38aa3b, v160
	v_exp_f32_e32 v113, v113
	v_fmamk_f32 v114, v114, 0x3e38aa3b, v160
	v_exp_f32_e32 v114, v114
	v_fmamk_f32 v115, v115, 0x3e38aa3b, v160
	v_cmp_gt_u32_e32 vcc, s75, v0
	v_add_u32_e32 v163, -1, v0
	v_exp_f32_e32 v115, v115
	v_fmamk_f32 v116, v116, 0x3e38aa3b, v160
	v_cndmask_b32_e32 v112, 0, v112, vcc
	v_cmp_gt_u32_e32 vcc, s75, v163
	v_add_u32_e32 v163, -2, v0
	v_exp_f32_e32 v116, v116
	v_fmamk_f32 v117, v117, 0x3e38aa3b, v160
	v_add_f32_e32 v162, 0, v112
	v_cndmask_b32_e32 v113, 0, v113, vcc
	v_cmp_gt_u32_e32 vcc, s75, v163
	v_add_u32_e32 v163, -3, v0
	v_exp_f32_e32 v117, v117
	v_fmamk_f32 v118, v118, 0x3e38aa3b, v160
	v_add_f32_e32 v162, v113, v162
	v_cndmask_b32_e32 v114, 0, v114, vcc
	v_cmp_gt_u32_e32 vcc, s75, v163
	v_add_u32_e32 v163, -4, v0
	v_exp_f32_e32 v118, v118
	v_fmamk_f32 v119, v119, 0x3e38aa3b, v160
	v_add_f32_e32 v162, v114, v162
	v_cndmask_b32_e32 v115, 0, v115, vcc
	v_cmp_gt_u32_e32 vcc, s75, v163
	v_add_u32_e32 v163, -5, v0
	v_exp_f32_e32 v119, v119
	v_fmamk_f32 v120, v120, 0x3e38aa3b, v160
	v_add_f32_e32 v162, v115, v162
	v_cndmask_b32_e32 v116, 0, v116, vcc
	v_cmp_gt_u32_e32 vcc, s75, v163
	v_add_u32_e32 v163, -6, v0
	v_exp_f32_e32 v120, v120
	v_fmamk_f32 v121, v121, 0x3e38aa3b, v160
	v_add_f32_e32 v162, v116, v162
	v_cndmask_b32_e32 v117, 0, v117, vcc
	v_cmp_gt_u32_e32 vcc, s75, v163
	v_add_u32_e32 v163, -7, v0
	v_exp_f32_e32 v121, v121
	v_fmamk_f32 v122, v122, 0x3e38aa3b, v160
	v_add_f32_e32 v162, v117, v162
	v_cndmask_b32_e32 v118, 0, v118, vcc
	v_cmp_gt_u32_e32 vcc, s75, v163
	v_add_u32_e32 v163, -16, v0
	v_exp_f32_e32 v122, v122
	v_fmamk_f32 v123, v123, 0x3e38aa3b, v160
	v_add_f32_e32 v162, v118, v162
	v_cndmask_b32_e32 v119, 0, v119, vcc
	v_cmp_gt_u32_e32 vcc, s75, v163
	v_subrev_u32_e32 v163, 17, v0
	v_exp_f32_e32 v123, v123
	v_fmamk_f32 v124, v124, 0x3e38aa3b, v160
	v_add_f32_e32 v162, v119, v162
	v_cndmask_b32_e32 v120, 0, v120, vcc
	v_cmp_gt_u32_e32 vcc, s75, v163
	v_subrev_u32_e32 v163, 18, v0
	v_exp_f32_e32 v124, v124
	v_fmamk_f32 v125, v125, 0x3e38aa3b, v160
	v_add_f32_e32 v162, v120, v162
	v_cndmask_b32_e32 v121, 0, v121, vcc
	v_cmp_gt_u32_e32 vcc, s75, v163
	v_subrev_u32_e32 v163, 19, v0
	v_exp_f32_e32 v125, v125
	v_fmamk_f32 v126, v126, 0x3e38aa3b, v160
	v_add_f32_e32 v162, v121, v162
	v_cndmask_b32_e32 v122, 0, v122, vcc
	v_cmp_gt_u32_e32 vcc, s75, v163
	v_subrev_u32_e32 v163, 20, v0
	v_exp_f32_e32 v126, v126
	v_fmac_f32_e32 v160, 0x3e38aa3b, v127
	v_add_f32_e32 v162, v122, v162
	v_cndmask_b32_e32 v123, 0, v123, vcc
	v_cmp_gt_u32_e32 vcc, s75, v163
	v_subrev_u32_e32 v163, 21, v0
	v_exp_f32_e32 v127, v160
	v_add_f32_e32 v162, v123, v162
	v_cndmask_b32_e32 v124, 0, v124, vcc
	v_cmp_gt_u32_e32 vcc, s75, v163
	v_subrev_u32_e32 v163, 22, v0
	v_add_f32_e32 v162, v124, v162
	v_cndmask_b32_e32 v125, 0, v125, vcc
	v_cmp_gt_u32_e32 vcc, s75, v163
	v_subrev_u32_e32 v160, 23, v0
	v_add_f32_e32 v162, v125, v162
	v_cndmask_b32_e32 v126, 0, v126, vcc
	v_cmp_gt_u32_e32 vcc, s75, v160
	v_add_f32_e32 v162, v126, v162
	v_cndmask_b32_e32 v127, 0, v127, vcc
	v_add_f32_e32 v160, v127, v162
	v_add_f32_e32 v177, v177, v160
	v_cvt_pk_bf16_f32 v112, v112, v113
	v_cvt_pk_bf16_f32 v113, v114, v115
	v_cvt_pk_bf16_f32 v114, v116, v117
	v_cvt_pk_bf16_f32 v115, v118, v119
	v_cvt_pk_bf16_f32 v116, v120, v121
	v_cvt_pk_bf16_f32 v118, v124, v125
	v_cvt_pk_bf16_f32 v117, v122, v123
	v_cvt_pk_bf16_f32 v119, v126, v127
	s_waitcnt lgkmcnt(0)
	s_nop 0
	v_mfma_f32_32x32x16_bf16 v[96:111], v[214:217], v[112:115], v[96:111]
	v_mfma_f32_32x32x16_bf16 v[80:95], v[222:225], v[112:115], v[80:95]
	v_mfma_f32_32x32x16_bf16 v[64:79], v[230:233], v[112:115], v[64:79]
	v_mfma_f32_32x32x16_bf16 v[48:63], v[248:251], v[112:115], v[48:63]
	v_mfma_f32_32x32x16_bf16 v[32:47], v[148:151], v[112:115], v[32:47]
	v_mfma_f32_32x32x16_bf16 v[16:31], v[156:159], v[112:115], v[16:31]
	v_mfma_f32_32x32x16_bf16 v[96:111], v[218:221], v[116:119], v[96:111]
	v_mfma_f32_32x32x16_bf16 v[80:95], v[226:229], v[116:119], v[80:95]
	v_mfma_f32_32x32x16_bf16 v[64:79], v[244:247], v[116:119], v[64:79]
	v_mfma_f32_32x32x16_bf16 v[48:63], v[164:167], v[116:119], v[48:63]
	v_mfma_f32_32x32x16_bf16 v[32:47], v[152:155], v[116:119], v[32:47]
	v_mfma_f32_32x32x16_bf16 v[16:31], v[200:203], v[116:119], v[16:31]
	v_subrev_u32_e32 v0, 32, v0
	s_cmp_lt_i32 s44, s43
	s_cbranch_scc1 .Ldil_g0top
.Ldil_exit:
	v_mul_u32_u24_e32 v199, 0x60, v243
	ds_read_b128 v[148:151], v199
	ds_read_b128 v[152:155], v199 offset:16
	ds_read_b128 v[156:159], v199 offset:32
	ds_read_b128 v[160:163], v199 offset:48
	ds_read_b128 v[164:167], v199 offset:64
	s_waitcnt lgkmcnt(0)
	s_branch .LBB0_878
